# compress MLP K-loop: per-wave W1 tile staged by LDS-DMA (global_load_lds) with row-contiguous XOR-swizzled lane mapping, then conflict-free ds_read_b128 fragments (8x fewer L1 tag lookups than direct
# speedup vs baseline: 1.0196x; 1.0018x over previous
.LBB0_85:
	s_or_b64 exec, exec, s[12:13]
	s_lshl_b32 s12, s4, 4
	s_lshl_b32 s5, s4, 3
	v_and_b32_e32 v35, 15, v4
	s_and_b32 s12, s12, 0xf0
	s_and_b32 s15, s5, 0x180
	v_or_b32_e32 v2, s12, v35
	s_movk_i32 s2, 0xff
	s_lshl_b32 s18, s10, 9
	v_lshlrev_b32_e32 v3, 4, v2
	v_cmp_ne_u32_e32 vcc, s2, v2
	v_mov_b32_e32 v2, 0xfe0
	s_or_b32 s18, s18, s15
	s_bfe_u32 s13, s4, 0x20006
	v_cndmask_b32_e32 v2, v2, v3, vcc
	s_ashr_i32 s19, s18, 31
	v_readlane_b32 s20, v254, 46
	s_lshr_b32 s14, s4, 4
	s_lshr_b32 s5, s4, 6
	s_lshl_b64 s[16:17], s[10:11], 20
	v_lshl_or_b32 v2, s13, 12, v2
	s_lshl_b64 s[18:19], s[18:19], 1
	v_readlane_b32 s22, v254, 48
	v_mul_u32_u24_e32 v2, 0x1400, v2
	v_readlane_b32 s23, v254, 49
	s_add_u32 s18, s22, s18
	v_ashrrev_i32_e32 v5, 2, v4
	v_lshlrev_b32_e32 v2, 1, v2
	v_mov_b32_e32 v3, v0
	s_addc_u32 s19, s23, s19
	v_lshl_add_u64 v[8:9], s[18:19], 0, v[2:3]
	v_bfi_b32 v2, -16, v5, v4
	v_readlane_b32 s2, v254, 28
	v_ashrrev_i32_e32 v3, 31, v2
	s_add_u32 s16, s2, s16
	v_readlane_b32 s2, v254, 29
	v_lshlrev_b64 v[2:3], 13, v[2:3]
	s_addc_u32 s17, s2, s17
	v_bfe_u32 v1, v4, 4, 2
	v_lshl_add_u64 v[10:11], s[16:17], 0, v[2:3]
	v_mov_b32_e32 v2, 0
	v_lshlrev_b32_e32 v14, 3, v1
	v_and_b32_e32 v34, -16, v5
	v_lshl_add_u32 v15, v1, 5, 0
	v_lshlrev_b32_e32 v6, 4, v1
	v_mov_b32_e32 v7, v0
	s_mov_b32 s15, 0
	v_mov_b32_e32 v3, v2
	v_mov_b32_e32 v4, v2
	v_mov_b32_e32 v5, v2
	s_waitcnt lgkmcnt(0)
	s_barrier
	v_readlane_b32 s21, v254, 47
	v_lshrrev_b32_e32 v144, 6, v214
	v_lshlrev_b32_e32 v145, 7, v144
	v_lshlrev_b32_e32 v147, 4, v217
	v_lshl_add_u32 v146, v144, 10, v147
	v_add_u32_e32 v146, 0x8000, v146
	v_add_u32_e32 v147, 0x8000, v147
	v_lshlrev_b32_e32 v150, 13, v144
	v_add_u32_e32 v150, 0xc000, v150
	v_and_b32_e32 v158, 15, v217
	v_lshrrev_b32_e32 v159, 4, v217
	v_and_b32_e32 v160, 7, v158
	v_lshrrev_b32_e32 v161, 3, v158
	v_xor_b32_e32 v159, v159, v160
	v_lshl_add_u32 v156, v161, 10, v150
	v_lshl_add_u32 v156, v160, 7, v156
	v_lshl_add_u32 v156, v159, 4, v156
	v_xor_b32_e32 v157, 64, v156
	v_lshrrev_b32_e32 v159, 3, v217
	v_and_b32_e32 v160, 7, v217
	v_xor_b32_e32 v160, v160, v159
	v_sub_u32_e32 v159, v159, v158
	v_lshlrev_b32_e32 v159, 13, v159
	v_lshl_add_u32 v159, v160, 4, v159
	v_add_u32_e32 v160, 0xffffff00, v159
	v_ashrrev_i32_e32 v161, 31, v160
	v_lshl_add_u64 v[152:153], v[10:11], 0, v[160:161]
	s_mov_b64 s[16:17], 0x10000
	v_lshl_add_u64 v[154:155], v[152:153], 0, s[16:17]
	v_lshlrev_b32_e32 v148, 6, v144
	v_mov_b32_e32 v149, 0x2700
	v_cmp_gt_u32_e32 vcc, 4, v144
	s_nop 1
	v_cndmask_b32_e32 v149, v149, v0, vcc
	v_add_u32_e32 v144, v148, v149
	s_cmpk_eq_i32 s15, 0x4000
	s_cbranch_scc1 .Lmy_cmp_nopf_p
	v_lshl_add_u64 v[12:13], v[8:9], 0, v[6:7]
	v_add_co_u32_e32 v28, vcc, 0x18691000, v12
	s_nop 1
	v_addc_co_u32_e32 v29, vcc, 0, v13, vcc
	s_nop 0
	v_add_co_u32_e32 v28, vcc, v28, v144
	s_nop 1
	v_addc_co_u32_e32 v29, vcc, 0, v29, vcc
	v_readfirstlane_b32 s16, v150
	global_load_dwordx4 v[64:67], v[28:29], off
	s_mov_b32 m0, s16
	s_nop 0
	global_load_lds_dwordx4 v[152:153], off
	s_add_i32 m0, s16, 1024
	s_nop 0
	global_load_lds_dwordx4 v[154:155], off
	s_add_i32 m0, s16, 1920
	s_nop 0
	global_load_lds_dwordx4 v[152:153], off offset:128
	s_add_i32 m0, s16, 2944
	s_nop 0
	global_load_lds_dwordx4 v[154:155], off offset:128
	s_add_i32 m0, s16, 3840
	s_nop 0
	global_load_lds_dwordx4 v[152:153], off offset:256
	s_add_i32 m0, s16, 4864
	s_nop 0
	global_load_lds_dwordx4 v[154:155], off offset:256
	s_add_i32 m0, s16, 5760
	s_nop 0
	global_load_lds_dwordx4 v[152:153], off offset:384
	s_add_i32 m0, s16, 6784
	s_nop 0
	global_load_lds_dwordx4 v[154:155], off offset:384
	s_mov_b64 s[16:17], 0x5000
	v_lshl_add_u64 v[8:9], v[8:9], 0, s[16:17]
	v_lshl_add_u64 v[152:153], v[152:153], 0, s[82:83]
	v_lshl_add_u64 v[154:155], v[154:155], 0, s[82:83]
.Lmy_cmp_nopf_p:
.LBB0_86:
	s_waitcnt vmcnt(0)
	v_add3_u32 v36, s15, v15, v145
	s_addk_i32 s15, 0x400
	ds_read_b128 v[128:131], v36
	ds_read_b128 v[132:135], v36 offset:16
	ds_read_b128 v[96:99], v156
	ds_read_b128 v[100:103], v157
	ds_read_b128 v[104:107], v156 offset:2048
	ds_read_b128 v[108:111], v157 offset:2048
	ds_read_b128 v[112:115], v156 offset:4096
	ds_read_b128 v[116:119], v157 offset:4096
	ds_read_b128 v[120:123], v156 offset:6144
	ds_read_b128 v[124:127], v157 offset:6144
	v_lshlrev_b32_e32 v20, 16, v64
	v_and_b32_e32 v21, 0xffff0000, v64
	v_lshlrev_b32_e32 v22, 16, v65
	v_and_b32_e32 v23, 0xffff0000, v65
	v_lshlrev_b32_e32 v24, 16, v66
	v_and_b32_e32 v25, 0xffff0000, v66
	v_lshlrev_b32_e32 v26, 16, v67
	v_and_b32_e32 v27, 0xffff0000, v67
	s_waitcnt lgkmcnt(0)
	s_cmpk_eq_i32 s15, 0x4000
	s_cbranch_scc1 .Lmy_cmp_nopf_a
	v_lshl_add_u64 v[12:13], v[8:9], 0, v[6:7]
	v_add_co_u32_e32 v28, vcc, 0x18691000, v12
	s_nop 1
	v_addc_co_u32_e32 v29, vcc, 0, v13, vcc
	s_nop 0
	v_add_co_u32_e32 v28, vcc, v28, v144
	s_nop 1
	v_addc_co_u32_e32 v29, vcc, 0, v29, vcc
	v_readfirstlane_b32 s16, v150
	global_load_dwordx4 v[64:67], v[28:29], off
	s_mov_b32 m0, s16
	s_nop 0
	global_load_lds_dwordx4 v[152:153], off
	s_add_i32 m0, s16, 1024
	s_nop 0
	global_load_lds_dwordx4 v[154:155], off
	s_add_i32 m0, s16, 1920
	s_nop 0
	global_load_lds_dwordx4 v[152:153], off offset:128
	s_add_i32 m0, s16, 2944
	s_nop 0
	global_load_lds_dwordx4 v[154:155], off offset:128
	s_add_i32 m0, s16, 3840
	s_nop 0
	global_load_lds_dwordx4 v[152:153], off offset:256
	s_add_i32 m0, s16, 4864
	s_nop 0
	global_load_lds_dwordx4 v[154:155], off offset:256
	s_add_i32 m0, s16, 5760
	s_nop 0
	global_load_lds_dwordx4 v[152:153], off offset:384
	s_add_i32 m0, s16, 6784
	s_nop 0
	global_load_lds_dwordx4 v[154:155], off offset:384
	s_mov_b64 s[16:17], 0x5000
	v_lshl_add_u64 v[8:9], v[8:9], 0, s[16:17]
	v_lshl_add_u64 v[152:153], v[152:153], 0, s[82:83]
	v_lshl_add_u64 v[154:155], v[154:155], 0, s[82:83]
.Lmy_cmp_nopf_a:
	v_pk_add_f32 v[20:21], v[128:129], v[20:21]
	v_pk_add_f32 v[22:23], v[130:131], v[22:23]
	v_pk_add_f32 v[24:25], v[132:133], v[24:25]
	v_pk_add_f32 v[26:27], v[134:135], v[26:27]
	v_cvt_pk_bf16_f32 v16, v20, v21
	v_cvt_pk_bf16_f32 v17, v22, v23
	v_cvt_pk_bf16_f32 v18, v24, v25
	v_cvt_pk_bf16_f32 v19, v26, v27
	ds_write_b128 v146, v[16:19]
	s_waitcnt lgkmcnt(0)
	s_barrier
	ds_read_b128 v[68:71], v147
	ds_read_b128 v[72:75], v147 offset:1024
	ds_read_b128 v[76:79], v147 offset:2048
	s_waitcnt lgkmcnt(2)
	v_mfma_f32_16x16x32_bf16 v[2:5], v[96:99], v[68:71], v[2:5]
	ds_read_b128 v[68:71], v147 offset:3072
	s_waitcnt lgkmcnt(2)
	v_mfma_f32_16x16x32_bf16 v[2:5], v[100:103], v[72:75], v[2:5]
	ds_read_b128 v[72:75], v147 offset:4096
	s_waitcnt lgkmcnt(2)
	v_mfma_f32_16x16x32_bf16 v[2:5], v[104:107], v[76:79], v[2:5]
	ds_read_b128 v[76:79], v147 offset:5120
	s_waitcnt lgkmcnt(2)
	v_mfma_f32_16x16x32_bf16 v[2:5], v[108:111], v[68:71], v[2:5]
	ds_read_b128 v[68:71], v147 offset:6144
	s_waitcnt lgkmcnt(2)
	v_mfma_f32_16x16x32_bf16 v[2:5], v[112:115], v[72:75], v[2:5]
	ds_read_b128 v[72:75], v147 offset:7168
	s_waitcnt lgkmcnt(2)
	v_mfma_f32_16x16x32_bf16 v[2:5], v[116:119], v[76:79], v[2:5]
	s_waitcnt lgkmcnt(1)
	v_mfma_f32_16x16x32_bf16 v[2:5], v[120:123], v[68:71], v[2:5]
	s_waitcnt lgkmcnt(0)
	v_mfma_f32_16x16x32_bf16 v[2:5], v[124:127], v[72:75], v[2:5]
	s_waitcnt vmcnt(0)
	v_add3_u32 v36, s15, v15, v145
	s_addk_i32 s15, 0x400
	ds_read_b128 v[128:131], v36
	ds_read_b128 v[132:135], v36 offset:16
	ds_read_b128 v[96:99], v156
	ds_read_b128 v[100:103], v157
	ds_read_b128 v[104:107], v156 offset:2048
	ds_read_b128 v[108:111], v157 offset:2048
	ds_read_b128 v[112:115], v156 offset:4096
	ds_read_b128 v[116:119], v157 offset:4096
	ds_read_b128 v[120:123], v156 offset:6144
	ds_read_b128 v[124:127], v157 offset:6144
	v_lshlrev_b32_e32 v20, 16, v64
	v_and_b32_e32 v21, 0xffff0000, v64
	v_lshlrev_b32_e32 v22, 16, v65
	v_and_b32_e32 v23, 0xffff0000, v65
	v_lshlrev_b32_e32 v24, 16, v66
	v_and_b32_e32 v25, 0xffff0000, v66
	v_lshlrev_b32_e32 v26, 16, v67
	v_and_b32_e32 v27, 0xffff0000, v67
	s_waitcnt lgkmcnt(0)
	s_cmpk_eq_i32 s15, 0x4000
	s_cbranch_scc1 .Lmy_cmp_nopf_b
	v_lshl_add_u64 v[12:13], v[8:9], 0, v[6:7]
	v_add_co_u32_e32 v28, vcc, 0x18691000, v12
	s_nop 1
	v_addc_co_u32_e32 v29, vcc, 0, v13, vcc
	s_nop 0
	v_add_co_u32_e32 v28, vcc, v28, v144
	s_nop 1
	v_addc_co_u32_e32 v29, vcc, 0, v29, vcc
	v_readfirstlane_b32 s16, v150
	global_load_dwordx4 v[64:67], v[28:29], off
	s_mov_b32 m0, s16
	s_nop 0
	global_load_lds_dwordx4 v[152:153], off
	s_add_i32 m0, s16, 1024
	s_nop 0
	global_load_lds_dwordx4 v[154:155], off
	s_add_i32 m0, s16, 1920
	s_nop 0
	global_load_lds_dwordx4 v[152:153], off offset:128
	s_add_i32 m0, s16, 2944
	s_nop 0
	global_load_lds_dwordx4 v[154:155], off offset:128
	s_add_i32 m0, s16, 3840
	s_nop 0
	global_load_lds_dwordx4 v[152:153], off offset:256
	s_add_i32 m0, s16, 4864
	s_nop 0
	global_load_lds_dwordx4 v[154:155], off offset:256
	s_add_i32 m0, s16, 5760
	s_nop 0
	global_load_lds_dwordx4 v[152:153], off offset:384
	s_add_i32 m0, s16, 6784
	s_nop 0
	global_load_lds_dwordx4 v[154:155], off offset:384
	s_mov_b64 s[16:17], 0x5000
	v_lshl_add_u64 v[8:9], v[8:9], 0, s[16:17]
	v_lshl_add_u64 v[152:153], v[152:153], 0, s[82:83]
	v_lshl_add_u64 v[154:155], v[154:155], 0, s[82:83]
.Lmy_cmp_nopf_b:
	v_pk_add_f32 v[20:21], v[128:129], v[20:21]
	v_pk_add_f32 v[22:23], v[130:131], v[22:23]
	v_pk_add_f32 v[24:25], v[132:133], v[24:25]
	v_pk_add_f32 v[26:27], v[134:135], v[26:27]
	v_cvt_pk_bf16_f32 v16, v20, v21
	v_cvt_pk_bf16_f32 v17, v22, v23
	v_cvt_pk_bf16_f32 v18, v24, v25
	v_cvt_pk_bf16_f32 v19, v26, v27
	ds_write_b128 v146, v[16:19] offset:8192
	s_waitcnt lgkmcnt(0)
	s_barrier
	ds_read_b128 v[68:71], v147 offset:8192
	ds_read_b128 v[72:75], v147 offset:9216
	ds_read_b128 v[76:79], v147 offset:10240
	s_waitcnt lgkmcnt(2)
	v_mfma_f32_16x16x32_bf16 v[2:5], v[96:99], v[68:71], v[2:5]
	ds_read_b128 v[68:71], v147 offset:11264
	s_waitcnt lgkmcnt(2)
	v_mfma_f32_16x16x32_bf16 v[2:5], v[100:103], v[72:75], v[2:5]
	ds_read_b128 v[72:75], v147 offset:12288
	s_waitcnt lgkmcnt(2)
	v_mfma_f32_16x16x32_bf16 v[2:5], v[104:107], v[76:79], v[2:5]
	ds_read_b128 v[76:79], v147 offset:13312
	s_waitcnt lgkmcnt(2)
	v_mfma_f32_16x16x32_bf16 v[2:5], v[108:111], v[68:71], v[2:5]
	ds_read_b128 v[68:71], v147 offset:14336
	s_waitcnt lgkmcnt(2)
	v_mfma_f32_16x16x32_bf16 v[2:5], v[112:115], v[72:75], v[2:5]
	ds_read_b128 v[72:75], v147 offset:15360
	s_waitcnt lgkmcnt(2)
	v_mfma_f32_16x16x32_bf16 v[2:5], v[116:119], v[76:79], v[2:5]
	s_waitcnt lgkmcnt(1)
	v_mfma_f32_16x16x32_bf16 v[2:5], v[120:123], v[68:71], v[2:5]
	s_waitcnt lgkmcnt(0)
	v_mfma_f32_16x16x32_bf16 v[2:5], v[124:127], v[72:75], v[2:5]
	s_cmpk_eq_i32 s15, 0x4000
	s_cbranch_scc0 .LBB0_86
	s_branch .Lmy_pad_cmp
.Lmy_tramp4:
	s_branch .LBB0_4
	s_nop 0
	s_nop 0
	s_nop 0
	s_nop 0
	s_nop 0
	s_nop 0
	s_nop 0
	s_nop 0
	s_nop 0
	s_nop 0
	s_nop 0
	s_nop 0
	s_nop 0
	s_nop 0
	s_nop 0
	s_nop 0
	s_nop 0
	s_nop 0
	s_nop 0
	s_nop 0
	s_nop 0
	s_nop 0
	s_nop 0
	s_nop 0
	s_nop 0
	s_nop 0
	s_nop 0
	s_nop 0
	s_nop 0
	s_nop 0
	s_nop 0
	s_nop 0
	s_nop 0
	s_nop 0
	s_nop 0
	s_nop 0
	s_nop 0
	s_nop 0
	s_nop 0
	s_nop 0
	s_nop 0
	s_nop 0
	s_nop 0
	s_nop 0
	s_nop 0
	s_nop 0
	s_nop 0
	s_nop 0
	s_nop 0
	s_nop 0
	s_nop 0
	s_nop 0
	s_nop 0
	s_nop 0
	s_nop 0
	s_nop 0
	s_nop 0
	s_nop 0
	s_nop 0
	s_nop 0
	s_nop 0
	s_nop 0
	s_nop 0
	s_nop 0
	s_nop 0
	s_nop 0
	s_nop 0
	s_nop 0
	s_nop 0
	s_nop 0
	s_nop 0
	s_nop 0
	s_nop 0
	s_nop 0
	s_nop 0
	s_nop 0
	s_nop 0
	s_nop 0
	s_nop 0
	s_nop 0
	s_nop 0
	s_nop 0
	s_nop 0
	s_nop 0
	s_nop 0
	s_nop 0
	s_nop 0
	s_nop 0
	s_nop 0
	s_nop 0
	s_nop 0
	s_nop 0
	s_nop 0
	s_nop 0
	s_nop 0
	s_nop 0
	s_nop 0
	s_nop 0
	s_nop 0
	s_nop 0
	s_nop 0
	s_nop 0
	s_nop 0
	s_nop 0
	s_nop 0
	s_nop 0
	s_nop 0
	s_nop 0
	s_nop 0
	s_nop 0
	s_nop 0
	s_nop 0
	s_nop 0
	s_nop 0
	s_nop 0
	s_nop 0
	s_nop 0
	s_nop 0
	s_nop 0
	s_nop 0
	s_nop 0
	s_nop 0
	s_nop 0
	s_nop 0
	s_nop 0
	s_nop 0
	s_nop 0
	s_nop 0
	s_nop 0
	s_nop 0
	s_nop 0
	s_nop 0
	s_nop 0
	s_nop 0
	s_nop 0
	s_nop 0
	s_nop 0
	s_nop 0
	s_nop 0
	s_nop 0
	s_nop 0
	s_nop 0
	s_nop 0
	s_nop 0
	s_nop 0
	s_nop 0
	s_nop 0
	s_nop 0
	s_nop 0
	s_nop 0
	s_nop 0
	s_nop 0
	s_nop 0
	s_nop 0
	s_nop 0
	s_nop 0
	s_nop 0
	s_nop 0
	s_nop 0
	s_nop 0
	s_nop 0
	s_nop 0
	s_nop 0
	s_nop 0
	s_nop 0
	s_nop 0
	s_nop 0
	s_nop 0
	s_nop 0
	s_nop 0
	s_nop 0
	s_nop 0
	s_nop 0
	s_nop 0
	s_nop 0
	s_nop 0
	s_nop 0
	s_nop 0
	s_nop 0
	s_nop 0
	s_nop 0
	s_nop 0
	s_nop 0
	s_nop 0
	s_nop 0
	s_nop 0
	s_nop 0
	s_nop 0
	s_nop 0
	s_nop 0
	s_nop 0
	s_nop 0
	s_nop 0
	s_nop 0
	s_nop 0
	s_nop 0
	s_nop 0
	s_nop 0
	s_nop 0
	s_nop 0
	s_nop 0
	s_nop 0
	s_nop 0
	s_nop 0
	s_nop 0
	s_nop 0
	s_nop 0
	s_nop 0
	s_nop 0
	s_nop 0
	s_nop 0
	s_nop 0
	s_nop 0
	s_nop 0
	s_nop 0
	s_nop 0
	s_nop 0
	s_nop 0
	s_nop 0
	s_nop 0
	s_nop 0
	s_nop 0
	s_nop 0
	s_nop 0
	s_nop 0
	s_nop 0
	s_nop 0
	s_nop 0
	s_nop 0
	s_nop 0
	s_nop 0
	s_nop 0
	s_nop 0
	s_nop 0
	s_nop 0
	s_nop 0
	s_nop 0
	s_nop 0
	s_nop 0
	s_nop 0
	s_nop 0
	s_nop 0
	s_nop 0
	s_nop 0
	s_nop 0
	s_nop 0
	s_nop 0
	s_nop 0
	s_nop 0
	s_nop 0
	s_nop 0
	s_nop 0
	s_nop 0
	s_nop 0
	s_nop 0
	s_nop 0
	s_nop 0
	s_nop 0
	s_nop 0
	s_nop 0
	s_nop 0
	s_nop 0
	s_nop 0
	s_nop 0
	s_nop 0
	s_nop 0
	s_nop 0
	s_nop 0
	s_nop 0
	s_nop 0
	s_nop 0
	s_nop 0
	s_nop 0
	s_nop 0
	s_nop 0
	s_nop 0
	s_nop 0
	s_nop 0
	s_nop 0
	s_nop 0
	s_nop 0
	s_nop 0
	s_nop 0
	s_nop 0
	s_nop 0
	s_nop 0
	s_nop 0
	s_nop 0
	s_nop 0
	s_nop 0
	s_nop 0
	s_nop 0
	s_nop 0
	s_nop 0
	s_nop 0
	s_nop 0
	s_nop 0
	s_nop 0
	s_nop 0
	s_nop 0
	s_nop 0
	s_nop 0
	s_nop 0
	s_nop 0
	s_nop 0
	s_nop 0
	s_nop 0
	s_nop 0
	s_nop 0
	s_nop 0
	s_nop 0
	s_nop 0
	s_nop 0
	s_nop 0
	s_nop 0
	s_nop 0
	s_nop 0
	s_nop 0
	s_nop 0
	s_nop 0
	s_nop 0
	s_nop 0
	s_nop 0
	s_nop 0
	s_nop 0
	s_nop 0
	s_nop 0
	s_nop 0
	s_nop 0
	s_nop 0
	s_nop 0
	s_nop 0
	s_nop 0
	s_nop 0
	s_nop 0
	s_nop 0
	s_nop 0
	s_nop 0
	s_nop 0
	s_nop 0
	s_nop 0
	s_nop 0
	s_nop 0
	s_nop 0
	s_nop 0
	s_nop 0
	s_nop 0
	s_nop 0
	s_nop 0
	s_nop 0
	s_nop 0
	s_nop 0
	s_nop 0
	s_nop 0
	s_nop 0
	s_nop 0
	s_nop 0
	s_nop 0
	s_nop 0
	s_nop 0
	s_nop 0
	s_nop 0
	s_nop 0
	s_nop 0
	s_nop 0
	s_nop 0
	s_nop 0
	s_nop 0
	s_nop 0
	s_nop 0
	s_nop 0
	s_nop 0
	s_nop 0
	s_nop 0
	s_nop 0
	s_nop 0
	s_nop 0
	s_nop 0
	s_nop 0
	s_nop 0
	s_nop 0
	s_nop 0
	s_nop 0
.Lmy_pad_cmp:
	s_nop 6
	v_mul_f32_e32 v8, 0x3d372713, v2
	v_mul_f32_e32 v9, 0x3d372713, v3
	v_mul_f32_e32 v10, 0x3d372713, v4
	v_mul_f32_e32 v11, 0x3d372713, v5
	v_mul_f32_e32 v8, v2, v8
	v_mul_f32_e32 v9, v3, v9
	v_mul_f32_e32 v10, v4, v10
	v_mul_f32_e32 v11, v5, v11
	v_fma_f32 v8, v2, v8, v2
	v_fma_f32 v9, v3, v9, v3
	v_fma_f32 v10, v4, v10, v4
	v_fma_f32 v11, v5, v11, v5
	v_mul_f32_e32 v8, 0xbfcc422a, v8
	v_mul_f32_e32 v9, 0xbfcc422a, v9
	v_mul_f32_e32 v10, 0xbfcc422a, v10
	v_mul_f32_e32 v11, 0xbfcc422a, v11
	v_mul_f32_e32 v8, 0x3fb8aa3b, v8
	v_mul_f32_e32 v9, 0x3fb8aa3b, v9
	v_mul_f32_e32 v10, 0x3fb8aa3b, v10
	v_mul_f32_e32 v11, 0x3fb8aa3b, v11
	v_exp_f32_e32 v8, v8
	v_exp_f32_e32 v9, v9
	v_exp_f32_e32 v10, v10
	v_exp_f32_e32 v11, v11
	v_add_f32_e32 v8, 1.0, v8
	v_add_f32_e32 v9, 1.0, v9
	v_add_f32_e32 v10, 1.0, v10
	v_add_f32_e32 v11, 1.0, v11
	v_rcp_f32_e32 v8, v8
	v_rcp_f32_e32 v9, v9
	v_rcp_f32_e32 v10, v10
	v_rcp_f32_e32 v11, v11
	s_and_b32 s14, s14, 3
	v_pk_mul_f32 v[2:3], v[2:3], v[8:9]
	v_or_b32_e32 v6, v34, v35
	v_pk_mul_f32 v[4:5], v[4:5], v[10:11]
	s_lshl_b64 s[10:11], s[10:11], 15
	v_readlane_b32 s15, v252, 27
	v_cvt_pk_bf16_f32 v2, v2, v3
	v_cvt_pk_bf16_f32 v3, v4, v5
	v_mad_u32_u24 v12, v35, s64, 0
	v_lshlrev_b32_e32 v4, 1, v34
	v_ashrrev_i32_e32 v7, 31, v6
	s_add_u32 s10, s15, s10
	v_readlane_b32 s15, v252, 28
	v_add3_u32 v4, v12, v4, v14
	s_addc_u32 s11, s15, s11
	ds_write_b64 v4, v[2:3] offset:16384
	v_lshlrev_b64 v[2:3], 8, v[6:7]
	v_lshl_add_u64 v[2:3], s[10:11], 0, v[2:3]
	v_lshlrev_b32_e32 v10, 1, v14
	v_mov_b32_e32 v11, v0
	v_lshl_add_u64 v[2:3], v[2:3], 0, v[10:11]
	s_waitcnt lgkmcnt(0)
	s_barrier
	global_load_dwordx4 v[26:29], v[2:3], off
	global_load_dwordx4 v[14:17], v[2:3], off offset:64
	global_load_dwordx4 v[6:9], v[2:3], off offset:128
	s_nop 0
	global_load_dwordx4 v[2:5], v[2:3], off offset:192
	v_add_u32_e32 v10, v12, v10
	ds_read_b128 v[30:33], v10 offset:16384
	ds_read_b128 v[22:25], v10 offset:16448
	ds_read_b128 v[18:21], v10 offset:16512
	ds_read_b128 v[10:13], v10 offset:16576
	s_cmpk_lt_u32 s4, 0x100
	s_mov_b64 s[10:11], -1
	s_cbranch_scc1 .LBB0_89
	s_waitcnt vmcnt(3) lgkmcnt(3)
	v_mfma_f32_16x16x32_bf16 v[36:39], v[30:33], v[26:29], 0
	v_readlane_b32 s10, v252, 21
	v_readlane_b32 s2, v252, 56
	v_readlane_b32 s11, v252, 22
	s_waitcnt vmcnt(2) lgkmcnt(2)
	v_mfma_f32_16x16x32_bf16 v[36:39], v[22:25], v[14:17], v[36:39]
	v_readlane_b32 s3, v252, 57
	s_mov_b32 s9, s3
	s_lshl_b32 s8, s12, 1
	s_waitcnt vmcnt(1) lgkmcnt(1)
	v_mfma_f32_16x16x32_bf16 v[36:39], v[18:21], v[6:9], v[36:39]
	v_writelane_b32 v252, s2, 56
	s_waitcnt vmcnt(0) lgkmcnt(0)
	v_mfma_f32_16x16x32_bf16 v[36:39], v[10:13], v[2:5], v[36:39]
	v_writelane_b32 v252, s3, 57
	s_nop 6
	v_cvt_pk_bf16_f32 v36, v36, v37
	v_cvt_pk_bf16_f32 v37, v38, v39
	v_lshl_or_b32 v38, s13, 9, v35
	v_lshl_or_b32 v38, s14, 7, v38
	v_add_u32_e32 v38, v38, v34
	v_ashrrev_i32_e32 v39, 31, v38
	v_lshlrev_b64 v[38:39], 9, v[38:39]
	v_lshl_add_u64 v[38:39], s[10:11], 0, v[38:39]
	v_lshl_add_u64 v[38:39], v[38:39], 0, s[8:9]
	s_mov_b64 s[10:11], 0
